# phase B GEMM mainloop rewritten: LDS-DMA staging + 4-set fragment ring read 3 phases ahead
# speedup vs baseline: 1.0556x; 1.0480x over previous
.LBB0_228:
	s_cmpk_lt_i32 s33, 0x1040
	s_mov_b64 s[0:1], -1
	s_cbranch_scc0 .LBB0_345
	s_and_b32 s76, s33, 63
	s_lshl_b32 s10, s76, 19
	s_ashr_i32 s16, s33, 6
	s_lshl_b32 s0, s16, 19
	s_add_u32 s68, s88, 0x3f80000
	s_addc_u32 s69, s89, 0
	s_add_u32 s68, s68, s10
	s_addc_u32 s69, s69, 0
	s_add_u32 s70, s88, s0
	s_addc_u32 s71, s89, 0
	v_readfirstlane_b32 s65, v168
	v_lshrrev_b32_e32 v206, 3, v168
	v_bfe_u32 v207, v168, 4, 3
	v_and_b32_e32 v208, 7, v168
	v_xor_b32_e32 v207, v207, v208
	v_lshlrev_b32_e32 v207, 4, v207
	s_lshr_b32 s65, s65, 6
	s_lshl_b32 s65, s65, 10
	s_movk_i32 s64, 0x1000
	v_mul_lo_u32 v206, v206, s64
	v_add_u32_e32 v206, v206, v207
	v_add_u32_e32 v207, 0x20000, v206
	v_add_u32_e32 v208, 0x40000, v206
	v_add_u32_e32 v209, 0x60000, v206
	v_add_u32_e32 v210, v156, v158
	v_add_u32_e32 v214, v157, v158
	v_add_u32_e32 v211, v156, v159
	v_add_u32_e32 v215, v157, v159
	v_add_u32_e32 v212, v156, v160
	v_add_u32_e32 v216, v157, v160
	v_add_u32_e32 v213, v156, v161
	v_add_u32_e32 v217, v157, v161
	v_mov_b32_e32 v0, 0
	v_mov_b32_e32 v1, v0
	v_mov_b32_e32 v2, v0
	v_mov_b32_e32 v3, v0
	v_mov_b32_e32 v4, v0
	v_mov_b32_e32 v5, v0
	v_mov_b32_e32 v6, v0
	v_mov_b32_e32 v7, v0
	v_mov_b32_e32 v8, v0
	v_mov_b32_e32 v9, v0
	v_mov_b32_e32 v10, v0
	v_mov_b32_e32 v11, v0
	v_mov_b32_e32 v12, v0
	v_mov_b32_e32 v13, v0
	v_mov_b32_e32 v14, v0
	v_mov_b32_e32 v15, v0
	v_mov_b32_e32 v16, v0
	v_mov_b32_e32 v17, v0
	v_mov_b32_e32 v18, v0
	v_mov_b32_e32 v19, v0
	v_mov_b32_e32 v20, v0
	v_mov_b32_e32 v21, v0
	v_mov_b32_e32 v22, v0
	v_mov_b32_e32 v23, v0
	v_mov_b32_e32 v24, v0
	v_mov_b32_e32 v25, v0
	v_mov_b32_e32 v26, v0
	v_mov_b32_e32 v27, v0
	v_mov_b32_e32 v28, v0
	v_mov_b32_e32 v29, v0
	v_mov_b32_e32 v30, v0
	v_mov_b32_e32 v31, v0
	v_mov_b32_e32 v32, v0
	v_mov_b32_e32 v33, v0
	v_mov_b32_e32 v34, v0
	v_mov_b32_e32 v35, v0
	v_mov_b32_e32 v36, v0
	v_mov_b32_e32 v37, v0
	v_mov_b32_e32 v38, v0
	v_mov_b32_e32 v39, v0
	v_mov_b32_e32 v40, v0
	v_mov_b32_e32 v41, v0
	v_mov_b32_e32 v42, v0
	v_mov_b32_e32 v43, v0
	v_mov_b32_e32 v44, v0
	v_mov_b32_e32 v45, v0
	v_mov_b32_e32 v46, v0
	v_mov_b32_e32 v47, v0
	v_mov_b32_e32 v48, v0
	v_mov_b32_e32 v49, v0
	v_mov_b32_e32 v50, v0
	v_mov_b32_e32 v51, v0
	v_mov_b32_e32 v52, v0
	v_mov_b32_e32 v53, v0
	v_mov_b32_e32 v54, v0
	v_mov_b32_e32 v55, v0
	v_mov_b32_e32 v56, v0
	v_mov_b32_e32 v57, v0
	v_mov_b32_e32 v58, v0
	v_mov_b32_e32 v59, v0
	v_mov_b32_e32 v60, v0
	v_mov_b32_e32 v61, v0
	v_mov_b32_e32 v62, v0
	v_mov_b32_e32 v63, v0
	s_add_u32 m0, s65, 0x0
	s_nop 0
	global_load_lds_dwordx4 v206, s[68:69]
	s_add_u32 m0, s65, 0x1000
	s_nop 0
	global_load_lds_dwordx4 v207, s[68:69]
	s_add_u32 m0, s65, 0x2000
	s_nop 0
	global_load_lds_dwordx4 v208, s[68:69]
	s_add_u32 m0, s65, 0x3000
	s_nop 0
	global_load_lds_dwordx4 v209, s[68:69]
	s_add_u32 m0, s65, 0x8000
	s_nop 0
	global_load_lds_dwordx4 v206, s[70:71]
	s_add_u32 m0, s65, 0x9000
	s_nop 0
	global_load_lds_dwordx4 v207, s[70:71]
	s_add_u32 m0, s65, 0xa000
	s_nop 0
	global_load_lds_dwordx4 v208, s[70:71]
	s_add_u32 m0, s65, 0xb000
	s_nop 0
	global_load_lds_dwordx4 v209, s[70:71]
	s_add_u32 s68, s68, 0x80
	s_addc_u32 s69, s69, 0
	s_add_u32 s70, s70, 0x80
	s_addc_u32 s71, s71, 0
	s_add_u32 m0, s65, 0x4000
	s_nop 0
	global_load_lds_dwordx4 v206, s[68:69]
	s_add_u32 m0, s65, 0x5000
	s_nop 0
	global_load_lds_dwordx4 v207, s[68:69]
	s_add_u32 m0, s65, 0x6000
	s_nop 0
	global_load_lds_dwordx4 v208, s[68:69]
	s_add_u32 m0, s65, 0x7000
	s_nop 0
	global_load_lds_dwordx4 v209, s[68:69]
	s_add_u32 m0, s65, 0xc000
	s_nop 0
	global_load_lds_dwordx4 v206, s[70:71]
	s_add_u32 m0, s65, 0xd000
	s_nop 0
	global_load_lds_dwordx4 v207, s[70:71]
	s_add_u32 m0, s65, 0xe000
	s_nop 0
	global_load_lds_dwordx4 v208, s[70:71]
	s_add_u32 m0, s65, 0xf000
	s_nop 0
	global_load_lds_dwordx4 v209, s[70:71]
	s_add_u32 s68, s68, 0x80
	s_addc_u32 s69, s69, 0
	s_add_u32 s70, s70, 0x80
	s_addc_u32 s71, s71, 0
	s_waitcnt vmcnt(8)
	s_barrier
	ds_read_b128 v[64:67], v210 offset:0
	ds_read_b128 v[68:71], v210 offset:4096
	ds_read_b128 v[72:75], v214 offset:32768
	ds_read_b128 v[76:79], v214 offset:36864
	ds_read_b128 v[80:83], v211 offset:0
	ds_read_b128 v[84:87], v211 offset:4096
	ds_read_b128 v[88:91], v215 offset:32768
	ds_read_b128 v[92:95], v215 offset:36864
	ds_read_b128 v[96:99], v212 offset:0
	ds_read_b128 v[100:103], v212 offset:4096
	ds_read_b128 v[104:107], v216 offset:32768
	ds_read_b128 v[108:111], v216 offset:36864
	s_mov_b32 s64, 0
.Lgm_loop_B:
	ds_read_b128 v[112:115], v213 offset:0
	ds_read_b128 v[116:119], v213 offset:4096
	ds_read_b128 v[120:123], v217 offset:32768
	ds_read_b128 v[124:127], v217 offset:36864
	s_waitcnt lgkmcnt(12)
	v_mfma_f32_32x32x16_bf16 v[48:63], v[64:67], v[72:75], v[48:63]
	v_mfma_f32_32x32x16_bf16 v[32:47], v[64:67], v[76:79], v[32:47]
	v_mfma_f32_32x32x16_bf16 v[16:31], v[68:71], v[72:75], v[16:31]
	v_mfma_f32_32x32x16_bf16 v[0:15], v[68:71], v[76:79], v[0:15]
	s_waitcnt vmcnt(0) lgkmcnt(0)
	s_barrier
	s_cmp_lt_u32 s64, 30
	s_cbranch_scc0 .Lgm_nodma0_B
	s_add_u32 m0, s65, 0x0
	s_nop 0
	global_load_lds_dwordx4 v206, s[68:69]
	s_add_u32 m0, s65, 0x1000
	s_nop 0
	global_load_lds_dwordx4 v207, s[68:69]
	s_add_u32 m0, s65, 0x2000
	s_nop 0
	global_load_lds_dwordx4 v208, s[68:69]
	s_add_u32 m0, s65, 0x3000
	s_nop 0
	global_load_lds_dwordx4 v209, s[68:69]
	s_add_u32 m0, s65, 0x8000
	s_nop 0
	global_load_lds_dwordx4 v206, s[70:71]
	s_add_u32 m0, s65, 0x9000
	s_nop 0
	global_load_lds_dwordx4 v207, s[70:71]
	s_add_u32 m0, s65, 0xa000
	s_nop 0
	global_load_lds_dwordx4 v208, s[70:71]
	s_add_u32 m0, s65, 0xb000
	s_nop 0
	global_load_lds_dwordx4 v209, s[70:71]
	s_add_u32 s68, s68, 0x80
	s_addc_u32 s69, s69, 0
	s_add_u32 s70, s70, 0x80
	s_addc_u32 s71, s71, 0
.Lgm_nodma0_B:
	ds_read_b128 v[64:67], v210 offset:16384
	ds_read_b128 v[68:71], v210 offset:20480
	ds_read_b128 v[72:75], v214 offset:49152
	ds_read_b128 v[76:79], v214 offset:53248
	v_mfma_f32_32x32x16_bf16 v[48:63], v[80:83], v[88:91], v[48:63]
	v_mfma_f32_32x32x16_bf16 v[32:47], v[80:83], v[92:95], v[32:47]
	v_mfma_f32_32x32x16_bf16 v[16:31], v[84:87], v[88:91], v[16:31]
	v_mfma_f32_32x32x16_bf16 v[0:15], v[84:87], v[92:95], v[0:15]
	ds_read_b128 v[80:83], v211 offset:16384
	ds_read_b128 v[84:87], v211 offset:20480
	ds_read_b128 v[88:91], v215 offset:49152
	ds_read_b128 v[92:95], v215 offset:53248
	v_mfma_f32_32x32x16_bf16 v[48:63], v[96:99], v[104:107], v[48:63]
	v_mfma_f32_32x32x16_bf16 v[32:47], v[96:99], v[108:111], v[32:47]
	v_mfma_f32_32x32x16_bf16 v[16:31], v[100:103], v[104:107], v[16:31]
	v_mfma_f32_32x32x16_bf16 v[0:15], v[100:103], v[108:111], v[0:15]
	ds_read_b128 v[96:99], v212 offset:16384
	ds_read_b128 v[100:103], v212 offset:20480
	ds_read_b128 v[104:107], v216 offset:49152
	ds_read_b128 v[108:111], v216 offset:53248
	v_mfma_f32_32x32x16_bf16 v[48:63], v[112:115], v[120:123], v[48:63]
	v_mfma_f32_32x32x16_bf16 v[32:47], v[112:115], v[124:127], v[32:47]
	v_mfma_f32_32x32x16_bf16 v[16:31], v[116:119], v[120:123], v[16:31]
	v_mfma_f32_32x32x16_bf16 v[0:15], v[116:119], v[124:127], v[0:15]
	ds_read_b128 v[112:115], v213 offset:16384
	ds_read_b128 v[116:119], v213 offset:20480
	ds_read_b128 v[120:123], v217 offset:49152
	ds_read_b128 v[124:127], v217 offset:53248
	s_waitcnt lgkmcnt(12)
	v_mfma_f32_32x32x16_bf16 v[48:63], v[64:67], v[72:75], v[48:63]
	v_mfma_f32_32x32x16_bf16 v[32:47], v[64:67], v[76:79], v[32:47]
	v_mfma_f32_32x32x16_bf16 v[16:31], v[68:71], v[72:75], v[16:31]
	v_mfma_f32_32x32x16_bf16 v[0:15], v[68:71], v[76:79], v[0:15]
	s_waitcnt vmcnt(0) lgkmcnt(0)
	s_barrier
	s_cmp_lt_u32 s64, 30
	s_cbranch_scc0 .Lgm_nodma1_B
	s_add_u32 m0, s65, 0x4000
	s_nop 0
	global_load_lds_dwordx4 v206, s[68:69]
	s_add_u32 m0, s65, 0x5000
	s_nop 0
	global_load_lds_dwordx4 v207, s[68:69]
	s_add_u32 m0, s65, 0x6000
	s_nop 0
	global_load_lds_dwordx4 v208, s[68:69]
	s_add_u32 m0, s65, 0x7000
	s_nop 0
	global_load_lds_dwordx4 v209, s[68:69]
	s_add_u32 m0, s65, 0xc000
	s_nop 0
	global_load_lds_dwordx4 v206, s[70:71]
	s_add_u32 m0, s65, 0xd000
	s_nop 0
	global_load_lds_dwordx4 v207, s[70:71]
	s_add_u32 m0, s65, 0xe000
	s_nop 0
	global_load_lds_dwordx4 v208, s[70:71]
	s_add_u32 m0, s65, 0xf000
	s_nop 0
	global_load_lds_dwordx4 v209, s[70:71]
	s_add_u32 s68, s68, 0x80
	s_addc_u32 s69, s69, 0
	s_add_u32 s70, s70, 0x80
	s_addc_u32 s71, s71, 0
.Lgm_nodma1_B:
	ds_read_b128 v[64:67], v210 offset:0
	ds_read_b128 v[68:71], v210 offset:4096
	ds_read_b128 v[72:75], v214 offset:32768
	ds_read_b128 v[76:79], v214 offset:36864
	v_mfma_f32_32x32x16_bf16 v[48:63], v[80:83], v[88:91], v[48:63]
	v_mfma_f32_32x32x16_bf16 v[32:47], v[80:83], v[92:95], v[32:47]
	v_mfma_f32_32x32x16_bf16 v[16:31], v[84:87], v[88:91], v[16:31]
	v_mfma_f32_32x32x16_bf16 v[0:15], v[84:87], v[92:95], v[0:15]
	ds_read_b128 v[80:83], v211 offset:0
	ds_read_b128 v[84:87], v211 offset:4096
	ds_read_b128 v[88:91], v215 offset:32768
	ds_read_b128 v[92:95], v215 offset:36864
	v_mfma_f32_32x32x16_bf16 v[48:63], v[96:99], v[104:107], v[48:63]
	v_mfma_f32_32x32x16_bf16 v[32:47], v[96:99], v[108:111], v[32:47]
	v_mfma_f32_32x32x16_bf16 v[16:31], v[100:103], v[104:107], v[16:31]
	v_mfma_f32_32x32x16_bf16 v[0:15], v[100:103], v[108:111], v[0:15]
	ds_read_b128 v[96:99], v212 offset:0
	ds_read_b128 v[100:103], v212 offset:4096
	ds_read_b128 v[104:107], v216 offset:32768
	ds_read_b128 v[108:111], v216 offset:36864
	v_mfma_f32_32x32x16_bf16 v[48:63], v[112:115], v[120:123], v[48:63]
	v_mfma_f32_32x32x16_bf16 v[32:47], v[112:115], v[124:127], v[32:47]
	v_mfma_f32_32x32x16_bf16 v[16:31], v[116:119], v[120:123], v[16:31]
	v_mfma_f32_32x32x16_bf16 v[0:15], v[116:119], v[124:127], v[0:15]
	s_add_u32 s64, s64, 2
	s_cmp_lt_u32 s64, 32
	s_cbranch_scc1 .Lgm_loop_B
	s_waitcnt lgkmcnt(0)
	s_barrier

.LBB0_1166:
	s_cmp_lt_i32 s90, 9
	s_cselect_b64 s[2:3], -1, 0
	s_and_b64 s[0:1], s[2:3], s[0:1]
	s_andn2_b64 vcc, exec, s[0:1]
	s_cbranch_vccnz .LBB0_1172
	s_andn2_b64 vcc, exec, s[8:9]
	s_cbranch_vccnz .LBB0_1172
	s_waitcnt vmcnt(7)
	v_and_b32_e32 v0, 63, v168
	s_waitcnt vmcnt(5)
	v_mov_b32_e32 v9, 0
	v_lshlrev_b32_e32 v8, 2, v0
	v_lshl_add_u64 v[2:3], s[88:89], 0, v[8:9]
	s_mov_b64 s[0:1], 0xe9d0000
	v_lshl_add_u64 v[10:11], v[2:3], 0, s[0:1]
	v_mbcnt_lo_u32_b32 v2, -1, 0
	v_mbcnt_hi_u32_b32 v2, -1, v2
	v_and_b32_e32 v3, 64, v2
	v_add_u32_e32 v3, 64, v3
	v_xor_b32_e32 v4, 32, v2
	v_cmp_lt_i32_e64 s[0:1], v4, v3
	v_lshlrev_b32_e32 v8, 4, v0
	s_waitcnt vmcnt(4)
	v_lshl_add_u64 v[12:13], s[50:51], 0, v[8:9]
	v_cndmask_b32_e64 v4, v2, v4, s[0:1]
	v_lshlrev_b32_e32 v56, 2, v4
	v_xor_b32_e32 v4, 16, v2
	v_cmp_lt_i32_e64 s[0:1], v4, v3
	s_waitcnt vmcnt(2)
	v_lshl_add_u64 v[22:23], s[84:85], 0, v[8:9]
	v_lshlrev_b32_e32 v8, 3, v0
	v_cndmask_b32_e64 v4, v2, v4, s[0:1]
	v_lshlrev_b32_e32 v57, 2, v4
	v_xor_b32_e32 v4, 8, v2
	v_cmp_lt_i32_e64 s[0:1], v4, v3
	v_or_b32_e32 v6, 0x180, v0
	v_or_b32_e32 v44, 0x1c0, v0
	v_cndmask_b32_e64 v4, v2, v4, s[0:1]
	v_lshlrev_b32_e32 v58, 2, v4
	v_xor_b32_e32 v4, 4, v2
	v_cmp_lt_i32_e64 s[0:1], v4, v3
	v_lshl_add_u64 v[34:35], s[88:89], 0, v[8:9]
	v_lshrrev_b32_e32 v1, 6, v168
	v_cndmask_b32_e64 v4, v2, v4, s[0:1]
	v_lshlrev_b32_e32 v59, 2, v4
	v_xor_b32_e32 v4, 2, v2
	v_cmp_lt_i32_e64 s[0:1], v4, v3
	s_waitcnt vmcnt(1)
	v_mov_b32_e32 v25, v9
	v_mov_b32_e32 v27, v9
	v_cndmask_b32_e64 v4, v2, v4, s[0:1]
	v_lshlrev_b32_e32 v60, 2, v4
	v_xor_b32_e32 v4, 1, v2
	v_cmp_lt_i32_e64 s[0:1], v4, v3
	s_waitcnt vmcnt(0)
	v_lshlrev_b32_e32 v28, 4, v6
	v_mov_b32_e32 v29, v9
	v_cndmask_b32_e64 v2, v2, v4, s[0:1]
	v_lshlrev_b32_e32 v61, 2, v2
	v_or_b32_e32 v2, 0x100, v0
	v_or_b32_e32 v4, 0x140, v0
	s_mov_b64 s[0:1], 0x9f80000
	v_lshlrev_b32_e32 v24, 4, v2
	v_lshlrev_b32_e32 v26, 4, v4
	v_lshlrev_b32_e32 v30, 4, v44
	v_mov_b32_e32 v31, v9
	v_lshl_add_u64 v[32:33], v[34:35], 0, s[0:1]
	s_mov_b64 s[0:1], 0xbf80000
	v_cmp_gt_u32_e32 vcc, 16, v0
	v_lshl_add_u64 v[14:15], s[50:51], 0, v[24:25]
	v_lshl_add_u64 v[16:17], s[50:51], 0, v[26:27]
	v_lshl_add_u64 v[18:19], s[50:51], 0, v[28:29]
	v_lshl_add_u64 v[20:21], s[50:51], 0, v[30:31]
	v_lshl_add_u64 v[24:25], s[84:85], 0, v[24:25]
	v_lshl_add_u64 v[26:27], s[84:85], 0, v[26:27]
	v_lshl_add_u64 v[28:29], s[84:85], 0, v[28:29]
	v_lshl_add_u64 v[30:31], s[84:85], 0, v[30:31]
	v_lshl_add_u64 v[34:35], v[34:35], 0, s[0:1]
	v_lshl_add_u32 v36, s94, 2, v1
	s_lshl_b32 s2, s92, 2
	v_mov_b32_e32 v62, 0x358637bd
	s_mov_b32 s3, 0x800000
	v_lshlrev_b32_e32 v8, 4, v0
	v_lshlrev_b32_e32 v38, 4, v2
	v_lshlrev_b32_e32 v40, 4, v4
	v_lshlrev_b32_e32 v42, 4, v6
	v_lshlrev_b32_e32 v44, 4, v44
	global_load_dwordx4 v[196:199], v[22:23], off offset:1024
	global_load_dwordx4 v[200:203], v[22:23], off offset:2048
	global_load_dwordx4 v[204:207], v[22:23], off offset:3072
	global_load_dwordx4 v[208:211], v[24:25], off
	global_load_dwordx4 v[212:215], v[26:27], off
	global_load_dwordx4 v[216:219], v[28:29], off
	global_load_dwordx4 v[220:223], v[30:31], off
	s_branch .LBB0_1170
.LBB0_1169:
	s_or_b64 exec, exec, s[0:1]
	v_lshlrev_b64 v[2:3], 12, v[36:37]
	v_lshl_add_u64 v[50:51], v[32:33], 0, v[2:3]
	v_lshl_add_u64 v[54:55], v[34:35], 0, v[2:3]
	global_load_dwordx2 v[52:53], v[50:51], off
	global_load_dwordx2 v[88:89], v[54:55], off
	global_load_dwordx2 v[90:91], v[50:51], off offset:512
	global_load_dwordx2 v[92:93], v[54:55], off offset:512
	global_load_dwordx2 v[94:95], v[50:51], off offset:1024
	global_load_dwordx2 v[96:97], v[54:55], off offset:1024
	global_load_dwordx2 v[98:99], v[50:51], off offset:1536
	global_load_dwordx2 v[100:101], v[54:55], off offset:1536
	global_load_dwordx2 v[104:105], v[50:51], off offset:2048
	global_load_dwordx2 v[106:107], v[54:55], off offset:2048
	global_load_dwordx2 v[108:109], v[50:51], off offset:2560
	global_load_dwordx2 v[110:111], v[54:55], off offset:2560
	s_waitcnt vmcnt(12)
	ds_bpermute_b32 v1, v56, v0
	v_lshlrev_b64 v[46:47], 13, v[36:37]
	v_lshl_add_u64 v[112:113], s[86:87], 0, v[46:47]
	v_lshl_add_u64 v[48:49], v[112:113], 0, v[8:9]
	v_mov_b32_e32 v39, v9
	s_waitcnt lgkmcnt(0)
	v_add_f32_e32 v0, v0, v1
	ds_bpermute_b32 v1, v57, v0
	v_lshl_add_u64 v[46:47], v[112:113], 0, v[38:39]
	v_mov_b32_e32 v43, v9
	v_mov_b32_e32 v45, v9
	s_add_i32 s94, s94, s92
	s_waitcnt lgkmcnt(0)
	v_add_f32_e32 v0, v0, v1
	ds_bpermute_b32 v1, v58, v0
	s_cmpk_lt_i32 s94, 0x800
	v_add_u32_e32 v36, s2, v36
	s_waitcnt lgkmcnt(0)
	v_add_f32_e32 v37, v0, v1
	global_load_dwordx4 v[0:3], v[12:13], off
	global_load_dwordx4 v[4:7], v[12:13], off offset:1024
	global_load_dwordx2 v[120:121], v[50:51], off offset:3072
	ds_bpermute_b32 v41, v59, v37
	global_load_dwordx2 v[122:123], v[54:55], off offset:3072
	global_load_dwordx4 v[64:67], v[12:13], off offset:2048
	global_load_dwordx4 v[68:71], v[12:13], off offset:3072
	global_load_dwordx2 v[124:125], v[50:51], off offset:3584
	global_load_dwordx2 v[126:127], v[54:55], off offset:3584
	global_load_dwordx4 v[72:75], v[48:49], off
	global_load_dwordx4 v[76:79], v[48:49], off offset:1024
	global_load_dwordx4 v[80:83], v[48:49], off offset:2048
	global_load_dwordx4 v[84:87], v[48:49], off offset:3072
	v_lshl_add_u64 v[54:55], v[112:113], 0, v[44:45]
	s_waitcnt lgkmcnt(0)
	v_add_f32_e32 v37, v37, v41
	ds_bpermute_b32 v41, v60, v37
	s_waitcnt lgkmcnt(0)
	v_add_f32_e32 v37, v37, v41
	ds_bpermute_b32 v41, v61, v37
	s_waitcnt lgkmcnt(0)
	v_add_f32_e32 v37, v37, v41
	v_mov_b32_e32 v41, v9
	v_lshl_add_u64 v[50:51], v[112:113], 0, v[40:41]
	v_fmamk_f32 v37, v37, 0x3a000000, v62
	v_mul_f32_e32 v39, 0x4b800000, v37
	v_cmp_gt_f32_e64 s[0:1], s3, v37
	s_waitcnt vmcnt(22)
	v_lshlrev_b32_e32 v132, 16, v88
	v_and_b32_e32 v133, 0xffff0000, v88
	v_lshlrev_b32_e32 v136, 16, v89
	v_and_b32_e32 v137, 0xffff0000, v89
	s_waitcnt vmcnt(21)
	v_lshlrev_b32_e32 v138, 16, v90
	s_waitcnt vmcnt(20)
	v_lshlrev_b32_e32 v140, 16, v92
	v_and_b32_e32 v139, 0xffff0000, v90
	v_and_b32_e32 v141, 0xffff0000, v92
	v_lshlrev_b32_e32 v142, 16, v91
	v_lshlrev_b32_e32 v144, 16, v93
	v_and_b32_e32 v143, 0xffff0000, v91
	v_and_b32_e32 v145, 0xffff0000, v93
	s_waitcnt vmcnt(19)
	v_lshlrev_b32_e32 v146, 16, v94
	v_and_b32_e32 v147, 0xffff0000, v94
	v_lshlrev_b32_e32 v150, 16, v95
	v_and_b32_e32 v151, 0xffff0000, v95
	global_load_dwordx4 v[88:91], v[14:15], off
	global_load_dwordx4 v[92:95], v[46:47], off
	s_waitcnt vmcnt(20)
	v_lshlrev_b32_e32 v148, 16, v96
	v_and_b32_e32 v149, 0xffff0000, v96
	v_lshlrev_b32_e32 v152, 16, v97
	v_and_b32_e32 v153, 0xffff0000, v97
	s_waitcnt vmcnt(19)
	v_lshlrev_b32_e32 v154, 16, v98
	s_waitcnt vmcnt(18)
	v_lshlrev_b32_e32 v156, 16, v100
	v_and_b32_e32 v155, 0xffff0000, v98
	v_and_b32_e32 v157, 0xffff0000, v100
	v_lshlrev_b32_e32 v158, 16, v99
	v_lshlrev_b32_e32 v160, 16, v101
	v_and_b32_e32 v159, 0xffff0000, v99
	v_and_b32_e32 v161, 0xffff0000, v101
	global_load_dwordx4 v[96:99], v[16:17], off
	global_load_dwordx4 v[100:103], v[50:51], off
	v_lshlrev_b32_e32 v130, 16, v52
	v_and_b32_e32 v131, 0xffff0000, v52
	v_lshlrev_b32_e32 v134, 16, v53
	v_and_b32_e32 v135, 0xffff0000, v53
	s_waitcnt vmcnt(19)
	v_lshlrev_b32_e32 v162, 16, v104
	s_waitcnt vmcnt(18)
	v_lshlrev_b32_e32 v164, 16, v106
	v_and_b32_e32 v163, 0xffff0000, v104
	v_and_b32_e32 v165, 0xffff0000, v106
	v_lshlrev_b32_e32 v166, 16, v105
	v_lshlrev_b32_e32 v168, 16, v107
	v_and_b32_e32 v167, 0xffff0000, v105
	v_and_b32_e32 v169, 0xffff0000, v107
	s_waitcnt vmcnt(17)
	v_lshlrev_b32_e32 v170, 16, v108
	s_waitcnt vmcnt(16)
	v_lshlrev_b32_e32 v172, 16, v110
	v_and_b32_e32 v171, 0xffff0000, v108
	v_and_b32_e32 v173, 0xffff0000, v110
	v_lshlrev_b32_e32 v174, 16, v109
	v_lshlrev_b32_e32 v176, 16, v111
	v_and_b32_e32 v175, 0xffff0000, v109
	v_and_b32_e32 v177, 0xffff0000, v111
	v_lshl_add_u64 v[52:53], v[112:113], 0, v[42:43]
	global_load_dwordx4 v[104:107], v[18:19], off
	global_load_dwordx4 v[108:111], v[52:53], off
	global_load_dwordx4 v[112:115], v[20:21], off
	global_load_dwordx4 v[116:119], v[54:55], off
	v_cndmask_b32_e64 v37, v37, v39, s[0:1]
	v_rsq_f32_e32 v37, v37
	s_waitcnt vmcnt(17)
	v_lshlrev_b32_e32 v178, 16, v120
	v_and_b32_e32 v179, 0xffff0000, v120
	v_lshlrev_b32_e32 v182, 16, v121
	v_mul_f32_e32 v39, 0x45800000, v37
	v_cndmask_b32_e64 v128, v37, v39, s[0:1]
	v_and_b32_e32 v183, 0xffff0000, v121
	v_pk_mul_f32 v[120:121], v[128:129], v[132:133] op_sel_hi:[0,1]
	s_waitcnt vmcnt(16)
	v_lshlrev_b32_e32 v180, 16, v122
	v_and_b32_e32 v181, 0xffff0000, v122
	v_lshlrev_b32_e32 v184, 16, v123
	v_and_b32_e32 v185, 0xffff0000, v123
	v_pk_mul_f32 v[0:1], v[0:1], v[120:121]
	global_load_dwordx4 v[120:123], v[22:23], off
	s_waitcnt vmcnt(12)
	v_pk_fma_f32 v[0:1], v[0:1], v[130:131], v[72:73]
	v_pk_mul_f32 v[130:131], v[128:129], v[136:137] op_sel_hi:[0,1]
	v_pk_mul_f32 v[2:3], v[130:131], v[2:3]
	v_pk_mul_f32 v[130:131], v[128:129], v[140:141] op_sel_hi:[0,1]
	v_pk_mul_f32 v[4:5], v[4:5], v[130:131]
	v_pk_mul_f32 v[130:131], v[128:129], v[144:145] op_sel_hi:[0,1]
	v_pk_mul_f32 v[6:7], v[130:131], v[6:7]
	v_pk_mul_f32 v[130:131], v[128:129], v[148:149] op_sel_hi:[0,1]
	v_pk_mul_f32 v[64:65], v[64:65], v[130:131]
	v_pk_mul_f32 v[130:131], v[128:129], v[152:153] op_sel_hi:[0,1]
	v_pk_mul_f32 v[66:67], v[130:131], v[66:67]
	v_pk_mul_f32 v[130:131], v[128:129], v[156:157] op_sel_hi:[0,1]
	v_pk_mul_f32 v[68:69], v[68:69], v[130:131]
	v_pk_mul_f32 v[130:131], v[128:129], v[160:161] op_sel_hi:[0,1]
	v_pk_mul_f32 v[70:71], v[130:131], v[70:71]
	v_pk_mul_f32 v[130:131], v[128:129], v[164:165] op_sel_hi:[0,1]
	s_waitcnt vmcnt(11)
	v_pk_fma_f32 v[4:5], v[4:5], v[138:139], v[76:77]
	v_pk_mul_f32 v[72:73], v[0:1], v[0:1]
	v_pk_fma_f32 v[2:3], v[2:3], v[134:135], v[74:75]
	v_pk_mul_f32 v[76:77], v[4:5], v[4:5]
	v_pk_fma_f32 v[6:7], v[6:7], v[142:143], v[78:79]
	v_pk_mul_f32 v[74:75], v[2:3], v[2:3]
	v_pk_mul_f32 v[78:79], v[6:7], v[6:7]
	v_add_f32_e32 v37, v76, v77
	v_add_f32_e32 v39, v72, v73
	s_waitcnt vmcnt(10)
	v_pk_fma_f32 v[64:65], v[64:65], v[146:147], v[80:81]
	v_add_f32_e32 v37, v37, v78
	s_waitcnt vmcnt(8)
	v_pk_mul_f32 v[88:89], v[88:89], v[130:131]
	v_add_f32_e32 v39, v39, v74
	s_waitcnt vmcnt(7)
	v_pk_fma_f32 v[88:89], v[88:89], v[162:163], v[92:93]
	v_pk_mul_f32 v[92:93], v[128:129], v[168:169] op_sel_hi:[0,1]
	v_pk_mul_f32 v[90:91], v[92:93], v[90:91]
	v_pk_mul_f32 v[92:93], v[128:129], v[172:173] op_sel_hi:[0,1]
	v_pk_fma_f32 v[90:91], v[90:91], v[166:167], v[94:95]
	v_pk_mul_f32 v[94:95], v[128:129], v[176:177] op_sel_hi:[0,1]
	v_pk_mul_f32 v[80:81], v[64:65], v[64:65]
	v_pk_fma_f32 v[66:67], v[66:67], v[150:151], v[82:83]
	v_add_f32_e32 v37, v37, v79
	v_add_f32_e32 v39, v39, v75
	v_lshlrev_b32_e32 v188, 16, v126
	s_waitcnt vmcnt(6)
	v_pk_mul_f32 v[92:93], v[96:97], v[92:93]
	v_pk_mul_f32 v[94:95], v[94:95], v[98:99]
	s_waitcnt vmcnt(5)
	v_pk_fma_f32 v[92:93], v[92:93], v[170:171], v[100:101]
	v_mov_b32_e32 v98, v89
	v_mov_b32_e32 v99, v93
	v_pk_fma_f32 v[94:95], v[94:95], v[174:175], v[102:103]
	v_mov_b32_e32 v96, v88
	v_mov_b32_e32 v97, v92
	v_pk_mul_f32 v[98:99], v[98:99], v[98:99]
	v_and_b32_e32 v189, 0xffff0000, v126
	v_pk_mul_f32 v[82:83], v[66:67], v[66:67]
	v_pk_fma_f32 v[96:97], v[96:97], v[96:97], v[98:99]
	v_mov_b32_e32 v98, v90
	v_mov_b32_e32 v99, v94
	v_add_f32_e32 v37, v39, v37
	v_add_f32_e32 v39, v80, v81
	v_pk_fma_f32 v[68:69], v[68:69], v[154:155], v[84:85]
	v_pk_fma_f32 v[96:97], v[98:99], v[98:99], v[96:97]
	v_pk_mul_f32 v[98:99], v[128:129], v[180:181] op_sel_hi:[0,1]
	v_pk_mul_f32 v[102:103], v[128:129], v[188:189] op_sel_hi:[0,1]
	v_add_f32_e32 v39, v39, v82
	v_lshlrev_b32_e32 v186, 16, v124
	v_and_b32_e32 v187, 0xffff0000, v124
	v_lshlrev_b32_e32 v126, 16, v127
	v_and_b32_e32 v127, 0xffff0000, v127
	v_pk_mul_f32 v[84:85], v[68:69], v[68:69]
	v_pk_fma_f32 v[70:71], v[70:71], v[158:159], v[86:87]
	v_mov_b32_e32 v100, v91
	v_mov_b32_e32 v101, v95
	s_waitcnt vmcnt(4)
	v_pk_mul_f32 v[98:99], v[104:105], v[98:99]
	s_waitcnt vmcnt(2)
	v_pk_mul_f32 v[102:103], v[112:113], v[102:103]
	v_add_f32_e32 v39, v39, v83
	v_pk_mul_f32 v[86:87], v[70:71], v[70:71]
	v_pk_fma_f32 v[96:97], v[100:101], v[100:101], v[96:97]
	v_pk_fma_f32 v[98:99], v[98:99], v[178:179], v[108:109]
	v_pk_mul_f32 v[100:101], v[128:129], v[184:185] op_sel_hi:[0,1]
	s_waitcnt vmcnt(1)
	v_pk_fma_f32 v[102:103], v[102:103], v[186:187], v[116:117]
	v_pk_mul_f32 v[104:105], v[128:129], v[126:127] op_sel_hi:[0,1]
	v_add_f32_e32 v37, v37, v39
	v_add_f32_e32 v39, v84, v85
	v_lshlrev_b32_e32 v124, 16, v125
	v_and_b32_e32 v125, 0xffff0000, v125
	v_pk_mul_f32 v[100:101], v[100:101], v[106:107]
	v_pk_mul_f32 v[104:105], v[104:105], v[114:115]
	v_mov_b32_e32 v108, v99
	v_mov_b32_e32 v109, v103
	v_add_f32_e32 v39, v39, v86
	v_pk_fma_f32 v[100:101], v[100:101], v[182:183], v[110:111]
	v_pk_fma_f32 v[104:105], v[104:105], v[124:125], v[118:119]
	v_mov_b32_e32 v106, v98
	v_mov_b32_e32 v107, v102
	v_pk_mul_f32 v[108:109], v[108:109], v[108:109]
	v_add_f32_e32 v39, v39, v87
	v_pk_fma_f32 v[106:107], v[106:107], v[106:107], v[108:109]
	v_mov_b32_e32 v108, v100
	v_mov_b32_e32 v109, v104
	v_add_f32_e32 v37, v37, v39
	v_mov_b32_e32 v110, v101
	v_mov_b32_e32 v111, v105
	v_pk_fma_f32 v[106:107], v[108:109], v[108:109], v[106:107]
	v_add_f32_e32 v37, v37, v96
	v_pk_fma_f32 v[106:107], v[110:111], v[110:111], v[106:107]
	v_add_f32_e32 v37, v37, v97
	v_add_f32_e32 v37, v37, v106
	v_add_f32_e32 v37, v37, v107
	ds_bpermute_b32 v39, v56, v37
	s_waitcnt lgkmcnt(0)
	v_add_f32_e32 v37, v37, v39
	ds_bpermute_b32 v39, v57, v37
	s_waitcnt lgkmcnt(0)
	v_add_f32_e32 v37, v37, v39
	ds_bpermute_b32 v39, v58, v37
	s_waitcnt lgkmcnt(0)
	v_add_f32_e32 v37, v37, v39
	ds_bpermute_b32 v39, v59, v37
	s_waitcnt lgkmcnt(0)
	v_add_f32_e32 v37, v37, v39
	ds_bpermute_b32 v39, v60, v37
	s_waitcnt lgkmcnt(0)
	v_add_f32_e32 v37, v37, v39
	ds_bpermute_b32 v39, v61, v37
	s_waitcnt lgkmcnt(0)
	v_add_f32_e32 v37, v37, v39
	v_fmamk_f32 v37, v37, 0x3a000000, v62
	v_mul_f32_e32 v39, 0x4b800000, v37
	v_cmp_gt_f32_e64 s[0:1], s3, v37
	s_nop 1
	v_cndmask_b32_e64 v37, v37, v39, s[0:1]
	v_rsq_f32_e32 v37, v37
	s_nop 0
	v_mul_f32_e32 v39, 0x45800000, v37
	v_cndmask_b32_e64 v72, v37, v39, s[0:1]
	s_waitcnt vmcnt(0)
	v_pk_mul_f32 v[224:225], v[0:1], v[72:73] op_sel_hi:[1,0]
	v_pk_mul_f32 v[226:227], v[2:3], v[72:73] op_sel_hi:[1,0]
	v_pk_mul_f32 v[224:225], v[120:121], v[224:225]
	v_pk_mul_f32 v[226:227], v[122:123], v[226:227]
	global_store_dwordx4 v[48:49], v[224:227], off
	v_pk_mul_f32 v[228:229], v[4:5], v[72:73] op_sel_hi:[1,0]
	v_pk_mul_f32 v[230:231], v[6:7], v[72:73] op_sel_hi:[1,0]
	v_pk_mul_f32 v[228:229], v[196:197], v[228:229]
	v_pk_mul_f32 v[230:231], v[198:199], v[230:231]
	global_store_dwordx4 v[48:49], v[228:231], off offset:1024
	v_pk_mul_f32 v[232:233], v[64:65], v[72:73] op_sel_hi:[1,0]
	v_pk_mul_f32 v[234:235], v[66:67], v[72:73] op_sel_hi:[1,0]
	v_pk_mul_f32 v[232:233], v[200:201], v[232:233]
	v_pk_mul_f32 v[234:235], v[202:203], v[234:235]
	global_store_dwordx4 v[48:49], v[232:235], off offset:2048
	v_pk_mul_f32 v[236:237], v[68:69], v[72:73] op_sel_hi:[1,0]
	v_pk_mul_f32 v[238:239], v[70:71], v[72:73] op_sel_hi:[1,0]
	v_pk_mul_f32 v[236:237], v[204:205], v[236:237]
	v_pk_mul_f32 v[238:239], v[206:207], v[238:239]
	global_store_dwordx4 v[48:49], v[236:239], off offset:3072
	v_pk_mul_f32 v[240:241], v[88:89], v[72:73] op_sel_hi:[1,0]
	v_pk_mul_f32 v[242:243], v[90:91], v[72:73] op_sel_hi:[1,0]
	v_pk_mul_f32 v[240:241], v[208:209], v[240:241]
	v_pk_mul_f32 v[242:243], v[210:211], v[242:243]
	global_store_dwordx4 v[46:47], v[240:243], off
	v_pk_mul_f32 v[244:245], v[92:93], v[72:73] op_sel_hi:[1,0]
	v_pk_mul_f32 v[246:247], v[94:95], v[72:73] op_sel_hi:[1,0]
	v_pk_mul_f32 v[244:245], v[212:213], v[244:245]
	v_pk_mul_f32 v[246:247], v[214:215], v[246:247]
	global_store_dwordx4 v[50:51], v[244:247], off
	v_pk_mul_f32 v[248:249], v[98:99], v[72:73] op_sel_hi:[1,0]
	v_pk_mul_f32 v[250:251], v[100:101], v[72:73] op_sel_hi:[1,0]
	v_pk_mul_f32 v[248:249], v[216:217], v[248:249]
	v_pk_mul_f32 v[250:251], v[218:219], v[250:251]
	global_store_dwordx4 v[52:53], v[248:251], off
	v_pk_mul_f32 v[252:253], v[102:103], v[72:73] op_sel_hi:[1,0]
	v_pk_mul_f32 v[254:255], v[104:105], v[72:73] op_sel_hi:[1,0]
	v_pk_mul_f32 v[252:253], v[220:221], v[252:253]
	v_pk_mul_f32 v[254:255], v[222:223], v[254:255]
	global_store_dwordx4 v[54:55], v[252:255], off
	s_cbranch_scc0 .LBB0_1172

	.amdhsa_kernel _Z4mega6Params
		.amdhsa_group_segment_fixed_size 0
		.amdhsa_private_segment_fixed_size 0
		.amdhsa_kernarg_size 480
		.amdhsa_user_sgpr_count 2
		.amdhsa_user_sgpr_dispatch_ptr 0
		.amdhsa_user_sgpr_queue_ptr 0
		.amdhsa_user_sgpr_kernarg_segment_ptr 1
		.amdhsa_user_sgpr_dispatch_id 0
		.amdhsa_user_sgpr_kernarg_preload_length 0
		.amdhsa_user_sgpr_kernarg_preload_offset 0
		.amdhsa_user_sgpr_private_segment_size 0
		.amdhsa_uses_dynamic_stack 0
		.amdhsa_enable_private_segment 0
		.amdhsa_system_sgpr_workgroup_id_x 1
		.amdhsa_system_sgpr_workgroup_id_y 0
		.amdhsa_system_sgpr_workgroup_id_z 0
		.amdhsa_system_sgpr_workgroup_info 0
		.amdhsa_system_vgpr_workitem_id 2
		.amdhsa_next_free_vgpr 256
		.amdhsa_next_free_sgpr 98
		.amdhsa_accum_offset 256
		.amdhsa_reserve_vcc 1
		.amdhsa_float_round_mode_32 0
		.amdhsa_float_round_mode_16_64 0
		.amdhsa_float_denorm_mode_32 3
		.amdhsa_float_denorm_mode_16_64 3
		.amdhsa_dx10_clamp 1
		.amdhsa_ieee_mode 1
		.amdhsa_fp16_overflow 0
		.amdhsa_tg_split 0
		.amdhsa_exception_fp_ieee_invalid_op 0
		.amdhsa_exception_fp_denorm_src 0
		.amdhsa_exception_fp_ieee_div_zero 0
		.amdhsa_exception_fp_ieee_overflow 0
		.amdhsa_exception_fp_ieee_underflow 0
		.amdhsa_exception_fp_ieee_inexact 0
		.amdhsa_exception_int_div_zero 0
	.end_amdhsa_kernel

amdhsa.kernels:
  - .agpr_count:     0
    .args:
      - .offset:         0
        .size:           224
        .value_kind:     by_value
      - .offset:         224
        .size:           4
        .value_kind:     hidden_block_count_x
      - .offset:         228
        .size:           4
        .value_kind:     hidden_block_count_y
      - .offset:         232
        .size:           4
        .value_kind:     hidden_block_count_z
      - .offset:         236
        .size:           2
        .value_kind:     hidden_group_size_x
      - .offset:         238
        .size:           2
        .value_kind:     hidden_group_size_y
      - .offset:         240
        .size:           2
        .value_kind:     hidden_group_size_z
      - .offset:         242
        .size:           2
        .value_kind:     hidden_remainder_x
      - .offset:         244
        .size:           2
        .value_kind:     hidden_remainder_y
      - .offset:         246
        .size:           2
        .value_kind:     hidden_remainder_z
      - .offset:         264
        .size:           8
        .value_kind:     hidden_global_offset_x
      - .offset:         272
        .size:           8
        .value_kind:     hidden_global_offset_y
      - .offset:         280
        .size:           8
        .value_kind:     hidden_global_offset_z
      - .offset:         288
        .size:           2
        .value_kind:     hidden_grid_dims
      - .offset:         312
        .size:           8
        .value_kind:     hidden_multigrid_sync_arg
      - .offset:         344
        .size:           4
        .value_kind:     hidden_dynamic_lds_size
    .group_segment_fixed_size: 0
    .kernarg_segment_align: 8
    .kernarg_segment_size: 480
    .language:       OpenCL C
    .language_version:
      - 2
      - 0
    .max_flat_workgroup_size: 256
    .name:           _Z4mega6Params
    .private_segment_fixed_size: 0
    .sgpr_count:     104
    .sgpr_spill_count: 2
    .symbol:         _Z4mega6Params.kd
    .uniform_work_group_size: 1
    .uses_dynamic_stack: false
    .vgpr_count:     256
    .vgpr_spill_count: 0
    .wavefront_size: 64
